# combo19 + GEMM K-loops: loop-control scalar updates moved in front of the iteration's last barrier (out of the load segment's head)
# baseline (speedup 1.0000x reference)
.LBB0_183:
	ds_read_b128 v[134:137], v157
	ds_read_b128 v[138:141], v157 offset:1024
	ds_read_b128 v[142:145], v157 offset:2048
	ds_read_b128 v[146:149], v157 offset:3072
	ds_read_b128 v[162:165], v158
	ds_read_b128 v[166:169], v158 offset:1024
	ds_read_b128 v[170:173], v158 offset:2048
	ds_read_b128 v[174:177], v158 offset:3072
	s_add_u32 s8, s6, 0xfff80080
	s_addc_u32 s9, s7, -1
	s_cmp_eq_u32 s87, 28
	s_cselect_b32 s9, s5, s9
	s_cselect_b32 s8, s39, s8
	s_cselect_b32 s11, s46, s53
	s_cselect_b32 s10, s47, s52
	v_mov_b32_e32 v128, v223
	ds_read_b128 v[178:181], v159
	ds_read_b128 v[182:185], v159 offset:1024
	ds_read_b128 v[186:189], v159 offset:2048
	ds_read_b128 v[190:193], v159 offset:3072
	ds_read_b128 v[194:197], v159 offset:4096
	ds_read_b128 v[198:201], v159 offset:5120
	ds_read_b128 v[210:213], v159 offset:6144
	ds_read_b128 v[214:217], v159 offset:7168
	s_add_i32 m0, s3, 0xc000
	s_nop 0
	global_load_lds_dwordx4 v128, s[6:7]
	v_mov_b32_e32 v128, v154
	s_add_i32 m0, s3, 0xe000
	s_nop 0
	global_load_lds_dwordx4 v128, s[6:7]
	s_waitcnt vmcnt(8)
	s_waitcnt lgkmcnt(0)
	s_barrier
	s_setprio 1
	v_mfma_scale_f32_16x16x128_f8f6f4 v[124:127], v[134:141], v[178:185], v[124:127], v160, v160 op_sel_hi:[0,0,0]
	v_mfma_scale_f32_16x16x128_f8f6f4 v[120:123], v[142:149], v[178:185], v[120:123], v160, v160 op_sel_hi:[0,0,0]
	v_mfma_scale_f32_16x16x128_f8f6f4 v[108:111], v[134:141], v[186:193], v[108:111], v160, v160 op_sel_hi:[0,0,0]
	v_mfma_scale_f32_16x16x128_f8f6f4 v[104:107], v[142:149], v[186:193], v[104:107], v160, v160 op_sel_hi:[0,0,0]
	v_mfma_scale_f32_16x16x128_f8f6f4 v[202:205], v[134:141], v[194:201], v[92:95], v160, v160 op_sel_hi:[0,0,0]
	v_mfma_scale_f32_16x16x128_f8f6f4 v[218:221], v[142:149], v[194:201], v[88:91], v160, v160 op_sel_hi:[0,0,0]
	v_mfma_scale_f32_16x16x128_f8f6f4 v[224:227], v[134:141], v[210:217], v[76:79], v160, v160 op_sel_hi:[0,0,0]
	v_mfma_scale_f32_16x16x128_f8f6f4 v[228:231], v[142:149], v[210:217], v[72:75], v160, v160 op_sel_hi:[0,0,0]
	s_setprio 0
	s_setprio 1
	v_mfma_scale_f32_16x16x128_f8f6f4 v[116:119], v[162:169], v[178:185], v[116:119], v160, v160 op_sel_hi:[0,0,0]
	v_mfma_scale_f32_16x16x128_f8f6f4 v[112:115], v[170:177], v[178:185], v[112:115], v160, v160 op_sel_hi:[0,0,0]
	v_mfma_scale_f32_16x16x128_f8f6f4 v[100:103], v[162:169], v[186:193], v[100:103], v160, v160 op_sel_hi:[0,0,0]
	v_mfma_scale_f32_16x16x128_f8f6f4 v[96:99], v[170:177], v[186:193], v[96:99], v160, v160 op_sel_hi:[0,0,0]
	v_mfma_scale_f32_16x16x128_f8f6f4 v[178:181], v[162:169], v[194:201], v[84:87], v160, v160 op_sel_hi:[0,0,0]
	v_mfma_scale_f32_16x16x128_f8f6f4 v[182:185], v[170:177], v[194:201], v[80:83], v160, v160 op_sel_hi:[0,0,0]
	v_mfma_scale_f32_16x16x128_f8f6f4 v[186:189], v[162:169], v[210:217], v[68:71], v160, v160 op_sel_hi:[0,0,0]
	v_mfma_scale_f32_16x16x128_f8f6f4 v[190:193], v[170:177], v[210:217], v[64:67], v160, v160 op_sel_hi:[0,0,0]
	s_setprio 0
	s_barrier
	v_mov_b32_e32 v128, v253
	s_add_i32 s89, s16, s18
	s_nop 2
	ds_read_b128 v[64:67], v159 offset:16384
	ds_read_b128 v[68:71], v159 offset:17408
	ds_read_b128 v[72:75], v159 offset:18432
	ds_read_b128 v[76:79], v159 offset:19456
	ds_read_b128 v[80:83], v159 offset:20480
	ds_read_b128 v[84:87], v159 offset:21504
	ds_read_b128 v[88:91], v159 offset:22528
	ds_read_b128 v[92:95], v159 offset:23552
	s_mov_b32 m0, s89
	s_nop 0
	global_load_lds_dwordx4 v128, s[10:11]
	v_mov_b32_e32 v128, v155
	s_add_i32 m0, s89, 0x2000
	s_add_u32 s94, s10, 0x80000
	global_load_lds_dwordx4 v128, s[10:11]
	s_addc_u32 s95, s11, 0
	v_mov_b32_e32 v128, v253
	s_add_i32 s89, s17, s18
	s_mov_b32 m0, s89
	s_nop 0
	global_load_lds_dwordx4 v128, s[94:95]
	v_mov_b32_e32 v128, v155
	s_add_i32 m0, s89, 0x2000
	s_nop 0
	global_load_lds_dwordx4 v128, s[94:95]
	v_mov_b32_e32 v128, v223
	s_mov_b32 m0, s3
	s_nop 0
	global_load_lds_dwordx4 v128, s[8:9]
	v_mov_b32_e32 v128, v154
	s_mov_b32 m0, s19
	s_nop 0
	global_load_lds_dwordx4 v128, s[8:9]
	s_waitcnt vmcnt(8)
	s_waitcnt lgkmcnt(0)
	s_barrier
	s_setprio 1
	v_mfma_scale_f32_16x16x128_f8f6f4 v[60:63], v[134:141], v[64:71], v[60:63], v160, v160 op_sel_hi:[0,0,0]
	v_mfma_scale_f32_16x16x128_f8f6f4 v[56:59], v[142:149], v[64:71], v[56:59], v160, v160 op_sel_hi:[0,0,0]
	v_mfma_scale_f32_16x16x128_f8f6f4 v[194:197], v[134:141], v[72:79], v[44:47], v160, v160 op_sel_hi:[0,0,0]
	v_mfma_scale_f32_16x16x128_f8f6f4 v[198:201], v[142:149], v[72:79], v[40:43], v160, v160 op_sel_hi:[0,0,0]
	v_mfma_scale_f32_16x16x128_f8f6f4 v[210:213], v[134:141], v[80:87], v[28:31], v160, v160 op_sel_hi:[0,0,0]
	v_mfma_scale_f32_16x16x128_f8f6f4 v[214:217], v[142:149], v[80:87], v[24:27], v160, v160 op_sel_hi:[0,0,0]
	v_mfma_scale_f32_16x16x128_f8f6f4 v[232:235], v[134:141], v[88:95], v[12:15], v160, v160 op_sel_hi:[0,0,0]
	v_mfma_scale_f32_16x16x128_f8f6f4 v[236:239], v[142:149], v[88:95], v[8:11], v160, v160 op_sel_hi:[0,0,0]
	s_setprio 0
	s_setprio 1
	v_mfma_scale_f32_16x16x128_f8f6f4 v[52:55], v[162:169], v[64:71], v[52:55], v160, v160 op_sel_hi:[0,0,0]
	v_mfma_scale_f32_16x16x128_f8f6f4 v[48:51], v[170:177], v[64:71], v[48:51], v160, v160 op_sel_hi:[0,0,0]
	v_mfma_scale_f32_16x16x128_f8f6f4 v[240:243], v[162:169], v[72:79], v[36:39], v160, v160 op_sel_hi:[0,0,0]
	v_mfma_scale_f32_16x16x128_f8f6f4 v[244:247], v[170:177], v[72:79], v[32:35], v160, v160 op_sel_hi:[0,0,0]
	v_mfma_scale_f32_16x16x128_f8f6f4 v[248:251], v[162:169], v[80:87], v[20:23], v160, v160 op_sel_hi:[0,0,0]
	v_mfma_scale_f32_16x16x128_f8f6f4 v[130:133], v[170:177], v[80:87], v[16:19], v160, v160 op_sel_hi:[0,0,0]
	v_mfma_scale_f32_16x16x128_f8f6f4 v[206:209], v[162:169], v[88:95], v[4:7], v160, v160 op_sel_hi:[0,0,0]
	v_mfma_scale_f32_16x16x128_f8f6f4 v[150:153], v[170:177], v[88:95], v[0:3], v160, v160 op_sel_hi:[0,0,0]
	s_setprio 0
	s_barrier
	s_add_i32 s89, 0, 0x18000
	v_add_u32_e32 v8, s89, v156
	s_add_i32 s96, 0, 0x1c000
	s_nop 1
	ds_read_b128 v[0:3], v8
	ds_read_b128 v[4:7], v8 offset:1024
	ds_read_b128 v[16:19], v8 offset:2048
	ds_read_b128 v[20:23], v8 offset:3072
	v_add_u32_e32 v8, s96, v156
	ds_read_b128 v[134:137], v8
	ds_read_b128 v[138:141], v8 offset:1024
	ds_read_b128 v[142:145], v8 offset:2048
	ds_read_b128 v[146:149], v8 offset:3072
	s_add_u32 s94, s8, 0x80000
	v_mov_b32_e32 v64, v223
	s_mov_b32 m0, s22
	ds_read_b128 v[8:11], v159 offset:32768
	ds_read_b128 v[12:15], v159 offset:33792
	ds_read_b128 v[24:27], v159 offset:34816
	ds_read_b128 v[28:31], v159 offset:35840
	ds_read_b128 v[32:35], v159 offset:36864
	ds_read_b128 v[36:39], v159 offset:37888
	ds_read_b128 v[40:43], v159 offset:38912
	ds_read_b128 v[44:47], v159 offset:39936
	s_addc_u32 s95, s9, 0
	s_nop 0
	global_load_lds_dwordx4 v64, s[94:95]
	v_mov_b32_e32 v64, v154
	s_mov_b32 m0, s24
	s_nop 0
	global_load_lds_dwordx4 v64, s[94:95]
	s_waitcnt vmcnt(8)
	s_waitcnt lgkmcnt(0)
	s_barrier
	s_setprio 1
	v_mfma_scale_f32_16x16x128_f8f6f4 v[124:127], v[0:7], v[8:15], v[124:127], v160, v160 op_sel_hi:[0,0,0]
	v_mfma_scale_f32_16x16x128_f8f6f4 v[120:123], v[16:23], v[8:15], v[120:123], v160, v160 op_sel_hi:[0,0,0]
	v_mfma_scale_f32_16x16x128_f8f6f4 v[108:111], v[0:7], v[24:31], v[108:111], v160, v160 op_sel_hi:[0,0,0]
	v_mfma_scale_f32_16x16x128_f8f6f4 v[104:107], v[16:23], v[24:31], v[104:107], v160, v160 op_sel_hi:[0,0,0]
	v_mfma_scale_f32_16x16x128_f8f6f4 v[92:95], v[0:7], v[32:39], v[202:205], v160, v160 op_sel_hi:[0,0,0]
	v_mfma_scale_f32_16x16x128_f8f6f4 v[88:91], v[16:23], v[32:39], v[218:221], v160, v160 op_sel_hi:[0,0,0]
	v_mfma_scale_f32_16x16x128_f8f6f4 v[76:79], v[0:7], v[40:47], v[224:227], v160, v160 op_sel_hi:[0,0,0]
	v_mfma_scale_f32_16x16x128_f8f6f4 v[72:75], v[16:23], v[40:47], v[228:231], v160, v160 op_sel_hi:[0,0,0]
	s_setprio 0
	s_setprio 1
	v_mfma_scale_f32_16x16x128_f8f6f4 v[116:119], v[134:141], v[8:15], v[116:119], v160, v160 op_sel_hi:[0,0,0]
	v_mfma_scale_f32_16x16x128_f8f6f4 v[112:115], v[142:149], v[8:15], v[112:115], v160, v160 op_sel_hi:[0,0,0]
	v_mfma_scale_f32_16x16x128_f8f6f4 v[100:103], v[134:141], v[24:31], v[100:103], v160, v160 op_sel_hi:[0,0,0]
	v_mfma_scale_f32_16x16x128_f8f6f4 v[96:99], v[142:149], v[24:31], v[96:99], v160, v160 op_sel_hi:[0,0,0]
	v_mfma_scale_f32_16x16x128_f8f6f4 v[84:87], v[134:141], v[32:39], v[178:181], v160, v160 op_sel_hi:[0,0,0]
	v_mfma_scale_f32_16x16x128_f8f6f4 v[80:83], v[142:149], v[32:39], v[182:185], v160, v160 op_sel_hi:[0,0,0]
	v_mfma_scale_f32_16x16x128_f8f6f4 v[68:71], v[134:141], v[40:47], v[186:189], v160, v160 op_sel_hi:[0,0,0]
	v_mfma_scale_f32_16x16x128_f8f6f4 v[64:67], v[142:149], v[40:47], v[190:193], v160, v160 op_sel_hi:[0,0,0]
	s_setprio 0
	s_barrier
	v_mov_b32_e32 v128, v253
	ds_read_b128 v[32:35], v159 offset:49152
	ds_read_b128 v[36:39], v159 offset:50176
	ds_read_b128 v[162:165], v159 offset:51200
	ds_read_b128 v[166:169], v159 offset:52224
	ds_read_b128 v[170:173], v159 offset:53248
	ds_read_b128 v[174:177], v159 offset:54272
	ds_read_b128 v[178:181], v159 offset:55296
	ds_read_b128 v[182:185], v159 offset:56320
	s_add_i32 s89, s89, s18
	v_lshl_add_u64 v[8:9], s[10:11], 0, v[128:129]
	v_lshl_add_u64 v[8:9], v[8:9], 0, s[26:27]
	s_mov_b32 m0, s89
	v_mov_b32_e32 v128, v155
	global_load_lds_dwordx4 v[8:9], off
	s_add_i32 m0, s89, 0x2000
	v_lshl_add_u64 v[8:9], s[10:11], 0, v[128:129]
	v_lshl_add_u64 v[8:9], v[8:9], 0, s[26:27]
	s_add_u32 s10, s10, 0x80080
	global_load_lds_dwordx4 v[8:9], off
	s_addc_u32 s11, s11, 0
	v_mov_b32_e32 v8, v253
	s_add_i32 s89, s96, s18
	s_mov_b32 m0, s89
	v_mov_b32_e32 v128, v223
	global_load_lds_dwordx4 v8, s[10:11]
	v_mov_b32_e32 v8, v155
	s_add_i32 m0, s89, 0x2000
	s_nop 0
	global_load_lds_dwordx4 v8, s[10:11]
	s_mov_b32 m0, s35
	v_lshl_add_u64 v[8:9], s[8:9], 0, v[128:129]
	v_lshl_add_u64 v[8:9], v[8:9], 0, s[26:27]
	v_mov_b32_e32 v128, v154
	global_load_lds_dwordx4 v[8:9], off
	s_mov_b32 m0, s44
	v_lshl_add_u64 v[8:9], s[8:9], 0, v[128:129]
	v_lshl_add_u64 v[8:9], v[8:9], 0, s[26:27]
	global_load_lds_dwordx4 v[8:9], off
	s_waitcnt vmcnt(8)
	s_waitcnt lgkmcnt(0)
	s_barrier
	s_setprio 1
	v_mfma_scale_f32_16x16x128_f8f6f4 v[60:63], v[0:7], v[32:39], v[60:63], v160, v160 op_sel_hi:[0,0,0]
	v_mfma_scale_f32_16x16x128_f8f6f4 v[56:59], v[16:23], v[32:39], v[56:59], v160, v160 op_sel_hi:[0,0,0]
	v_mfma_scale_f32_16x16x128_f8f6f4 v[44:47], v[0:7], v[162:169], v[194:197], v160, v160 op_sel_hi:[0,0,0]
	v_mfma_scale_f32_16x16x128_f8f6f4 v[40:43], v[16:23], v[162:169], v[198:201], v160, v160 op_sel_hi:[0,0,0]
	v_mfma_scale_f32_16x16x128_f8f6f4 v[28:31], v[0:7], v[170:177], v[210:213], v160, v160 op_sel_hi:[0,0,0]
	v_mfma_scale_f32_16x16x128_f8f6f4 v[24:27], v[16:23], v[170:177], v[214:217], v160, v160 op_sel_hi:[0,0,0]
	v_mfma_scale_f32_16x16x128_f8f6f4 v[12:15], v[0:7], v[178:185], v[232:235], v160, v160 op_sel_hi:[0,0,0]
	v_mfma_scale_f32_16x16x128_f8f6f4 v[8:11], v[16:23], v[178:185], v[236:239], v160, v160 op_sel_hi:[0,0,0]
	s_setprio 0
	s_setprio 1
	v_mfma_scale_f32_16x16x128_f8f6f4 v[52:55], v[134:141], v[32:39], v[52:55], v160, v160 op_sel_hi:[0,0,0]
	v_mfma_scale_f32_16x16x128_f8f6f4 v[48:51], v[142:149], v[32:39], v[48:51], v160, v160 op_sel_hi:[0,0,0]
	v_mfma_scale_f32_16x16x128_f8f6f4 v[36:39], v[134:141], v[162:169], v[240:243], v160, v160 op_sel_hi:[0,0,0]
	v_mfma_scale_f32_16x16x128_f8f6f4 v[32:35], v[142:149], v[162:169], v[244:247], v160, v160 op_sel_hi:[0,0,0]
	v_mfma_scale_f32_16x16x128_f8f6f4 v[20:23], v[134:141], v[170:177], v[248:251], v160, v160 op_sel_hi:[0,0,0]
	v_mfma_scale_f32_16x16x128_f8f6f4 v[16:19], v[142:149], v[170:177], v[130:133], v160, v160 op_sel_hi:[0,0,0]
	v_mfma_scale_f32_16x16x128_f8f6f4 v[4:7], v[134:141], v[178:185], v[206:209], v160, v160 op_sel_hi:[0,0,0]
	v_mfma_scale_f32_16x16x128_f8f6f4 v[0:3], v[142:149], v[178:185], v[150:153], v160, v160 op_sel_hi:[0,0,0]
	s_setprio 0
	s_add_i32 s87, s87, 2
	s_add_u32 s6, s6, 0x100
	s_addc_u32 s7, s7, 0
	s_add_u32 s52, s52, 0x100
	s_addc_u32 s53, s53, 0
	s_cmp_gt_u32 s87, 29
	s_barrier
	s_cbranch_scc0 .LBB0_183
	s_and_b64 vcc, exec, s[28:29]
	s_cbranch_vccz .LBB0_186
	s_barrier

.LBB0_601:
	ds_read_b128 v[128:131], v173
	ds_read_b128 v[132:135], v173 offset:1024
	ds_read_b128 v[154:157], v173 offset:2048
	ds_read_b128 v[158:161], v173 offset:3072
	ds_read_b128 v[162:165], v174
	ds_read_b128 v[166:169], v174 offset:1024
	ds_read_b128 v[176:179], v174 offset:2048
	ds_read_b128 v[180:183], v174 offset:3072
	s_add_u32 s8, s6, 0xfff00080
	s_addc_u32 s9, s7, -1
	s_cmp_eq_u32 s52, 60
	s_cselect_b32 s11, s5, s9
	s_cselect_b32 s10, s27, s8
	s_cselect_b32 s9, s38, s47
	s_cselect_b32 s8, s39, s46
	v_lshl_add_u64 v[170:171], s[6:7], 0, v[146:147]
	s_add_i32 m0, s77, 0xc000
	ds_read_b128 v[184:187], v175
	ds_read_b128 v[188:191], v175 offset:1024
	ds_read_b128 v[192:195], v175 offset:2048
	ds_read_b128 v[196:199], v175 offset:3072
	ds_read_b128 v[200:203], v175 offset:4096
	ds_read_b128 v[204:207], v175 offset:5120
	ds_read_b128 v[208:211], v175 offset:6144
	ds_read_b128 v[212:215], v175 offset:7168
	global_load_lds_dwordx4 v[170:171], off
	v_lshl_add_u64 v[170:171], s[6:7], 0, v[148:149]
	s_add_i32 m0, s77, 0xe000
	s_nop 0
	global_load_lds_dwordx4 v[170:171], off
	s_waitcnt vmcnt(8)
	s_waitcnt lgkmcnt(0)
	s_barrier
	s_setprio 1
	v_mfma_f32_16x16x32_f16 v[124:127], v[128:131], v[184:187], v[124:127]
	v_mfma_f32_16x16x32_f16 v[120:123], v[154:157], v[184:187], v[120:123]
	v_mfma_f32_16x16x32_f16 v[108:111], v[128:131], v[192:195], v[108:111]
	v_mfma_f32_16x16x32_f16 v[104:107], v[154:157], v[192:195], v[104:107]
	v_mfma_f32_16x16x32_f16 v[92:95], v[128:131], v[200:203], v[92:95]
	v_mfma_f32_16x16x32_f16 v[88:91], v[154:157], v[200:203], v[88:91]
	v_mfma_f32_16x16x32_f16 v[76:79], v[128:131], v[208:211], v[76:79]
	v_mfma_f32_16x16x32_f16 v[72:75], v[154:157], v[208:211], v[72:75]
	v_mfma_f32_16x16x32_f16 v[124:127], v[132:135], v[188:191], v[124:127]
	v_mfma_f32_16x16x32_f16 v[120:123], v[158:161], v[188:191], v[120:123]
	v_mfma_f32_16x16x32_f16 v[108:111], v[132:135], v[196:199], v[108:111]
	v_mfma_f32_16x16x32_f16 v[104:107], v[158:161], v[196:199], v[104:107]
	v_mfma_f32_16x16x32_f16 v[92:95], v[132:135], v[204:207], v[92:95]
	v_mfma_f32_16x16x32_f16 v[88:91], v[158:161], v[204:207], v[88:91]
	v_mfma_f32_16x16x32_f16 v[76:79], v[132:135], v[212:215], v[76:79]
	v_mfma_f32_16x16x32_f16 v[72:75], v[158:161], v[212:215], v[72:75]
	s_setprio 0
	s_setprio 1
	v_mfma_f32_16x16x32_f16 v[116:119], v[162:165], v[184:187], v[116:119]
	v_mfma_f32_16x16x32_f16 v[112:115], v[176:179], v[184:187], v[112:115]
	v_mfma_f32_16x16x32_f16 v[100:103], v[162:165], v[192:195], v[100:103]
	v_mfma_f32_16x16x32_f16 v[96:99], v[176:179], v[192:195], v[96:99]
	v_mfma_f32_16x16x32_f16 v[84:87], v[162:165], v[200:203], v[84:87]
	v_mfma_f32_16x16x32_f16 v[80:83], v[176:179], v[200:203], v[80:83]
	v_mfma_f32_16x16x32_f16 v[68:71], v[162:165], v[208:211], v[68:71]
	v_mfma_f32_16x16x32_f16 v[64:67], v[176:179], v[208:211], v[64:67]
	v_mfma_f32_16x16x32_f16 v[116:119], v[166:169], v[188:191], v[116:119]
	v_mfma_f32_16x16x32_f16 v[112:115], v[180:183], v[188:191], v[112:115]
	v_mfma_f32_16x16x32_f16 v[100:103], v[166:169], v[196:199], v[100:103]
	v_mfma_f32_16x16x32_f16 v[96:99], v[180:183], v[196:199], v[96:99]
	v_mfma_f32_16x16x32_f16 v[84:87], v[166:169], v[204:207], v[84:87]
	v_mfma_f32_16x16x32_f16 v[80:83], v[180:183], v[204:207], v[80:83]
	v_mfma_f32_16x16x32_f16 v[68:71], v[166:169], v[212:215], v[68:71]
	v_mfma_f32_16x16x32_f16 v[64:67], v[180:183], v[212:215], v[64:67]
	s_setprio 0
	s_barrier
	s_add_i32 s53, s45, s23
	v_lshl_add_u64 v[170:171], s[8:9], 0, v[138:139]
	s_mov_b32 m0, s53
	ds_read_b128 v[184:187], v175 offset:16384
	ds_read_b128 v[188:191], v175 offset:17408
	ds_read_b128 v[192:195], v175 offset:18432
	ds_read_b128 v[196:199], v175 offset:19456
	ds_read_b128 v[200:203], v175 offset:20480
	ds_read_b128 v[204:207], v175 offset:21504
	ds_read_b128 v[208:211], v175 offset:22528
	ds_read_b128 v[212:215], v175 offset:23552
	global_load_lds_dwordx4 v[170:171], off
	s_add_i32 m0, s53, 0x2000
	s_add_u32 s94, s8, 0x100000
	v_lshl_add_u64 v[216:217], s[8:9], 0, v[142:143]
	s_addc_u32 s95, s9, 0
	s_add_i32 s53, s34, s23
	global_load_lds_dwordx4 v[216:217], off
	v_lshl_add_u64 v[218:219], s[94:95], 0, v[138:139]
	s_mov_b32 m0, s53
	v_lshl_add_u64 v[220:221], s[10:11], 0, v[140:141]
	global_load_lds_dwordx4 v[218:219], off
	v_lshl_add_u64 v[218:219], s[94:95], 0, v[142:143]
	s_add_i32 m0, s53, 0x2000
	s_nop 0
	global_load_lds_dwordx4 v[218:219], off
	v_lshl_add_u64 v[218:219], s[10:11], 0, v[136:137]
	s_mov_b32 m0, s77
	s_nop 0
	global_load_lds_dwordx4 v[218:219], off
	s_mov_b32 m0, s85
	s_nop 0
	global_load_lds_dwordx4 v[220:221], off
	s_waitcnt vmcnt(8)
	s_waitcnt lgkmcnt(0)
	s_barrier
	s_setprio 1
	v_mfma_f32_16x16x32_f16 v[60:63], v[128:131], v[184:187], v[60:63]
	v_mfma_f32_16x16x32_f16 v[56:59], v[154:157], v[184:187], v[56:59]
	v_mfma_f32_16x16x32_f16 v[44:47], v[128:131], v[192:195], v[44:47]
	v_mfma_f32_16x16x32_f16 v[40:43], v[154:157], v[192:195], v[40:43]
	v_mfma_f32_16x16x32_f16 v[28:31], v[128:131], v[200:203], v[28:31]
	v_mfma_f32_16x16x32_f16 v[24:27], v[154:157], v[200:203], v[24:27]
	v_mfma_f32_16x16x32_f16 v[12:15], v[128:131], v[208:211], v[12:15]
	v_mfma_f32_16x16x32_f16 v[8:11], v[154:157], v[208:211], v[8:11]
	v_mfma_f32_16x16x32_f16 v[60:63], v[132:135], v[188:191], v[60:63]
	v_mfma_f32_16x16x32_f16 v[56:59], v[158:161], v[188:191], v[56:59]
	v_mfma_f32_16x16x32_f16 v[44:47], v[132:135], v[196:199], v[44:47]
	v_mfma_f32_16x16x32_f16 v[40:43], v[158:161], v[196:199], v[40:43]
	v_mfma_f32_16x16x32_f16 v[28:31], v[132:135], v[204:207], v[28:31]
	v_mfma_f32_16x16x32_f16 v[24:27], v[158:161], v[204:207], v[24:27]
	v_mfma_f32_16x16x32_f16 v[12:15], v[132:135], v[212:215], v[12:15]
	v_mfma_f32_16x16x32_f16 v[8:11], v[158:161], v[212:215], v[8:11]
	s_setprio 0
	s_setprio 1
	v_mfma_f32_16x16x32_f16 v[52:55], v[162:165], v[184:187], v[52:55]
	v_mfma_f32_16x16x32_f16 v[48:51], v[176:179], v[184:187], v[48:51]
	v_mfma_f32_16x16x32_f16 v[36:39], v[162:165], v[192:195], v[36:39]
	v_mfma_f32_16x16x32_f16 v[32:35], v[176:179], v[192:195], v[32:35]
	v_mfma_f32_16x16x32_f16 v[20:23], v[162:165], v[200:203], v[20:23]
	v_mfma_f32_16x16x32_f16 v[16:19], v[176:179], v[200:203], v[16:19]
	v_mfma_f32_16x16x32_f16 v[4:7], v[162:165], v[208:211], v[4:7]
	v_mfma_f32_16x16x32_f16 v[0:3], v[176:179], v[208:211], v[0:3]
	v_mfma_f32_16x16x32_f16 v[52:55], v[166:169], v[188:191], v[52:55]
	v_mfma_f32_16x16x32_f16 v[48:51], v[180:183], v[188:191], v[48:51]
	v_mfma_f32_16x16x32_f16 v[36:39], v[166:169], v[196:199], v[36:39]
	v_mfma_f32_16x16x32_f16 v[32:35], v[180:183], v[196:199], v[32:35]
	v_mfma_f32_16x16x32_f16 v[20:23], v[166:169], v[204:207], v[20:23]
	v_mfma_f32_16x16x32_f16 v[16:19], v[180:183], v[204:207], v[16:19]
	v_mfma_f32_16x16x32_f16 v[4:7], v[166:169], v[212:215], v[4:7]
	v_mfma_f32_16x16x32_f16 v[0:3], v[180:183], v[212:215], v[0:3]
	s_setprio 0
	s_barrier
	s_add_i32 s53, 0, 0x18000
	v_add_u32_e32 v144, s53, v172
	s_add_i32 s87, 0, 0x1c000
	ds_read_b128 v[128:131], v144
	ds_read_b128 v[132:135], v144 offset:1024
	ds_read_b128 v[154:157], v144 offset:2048
	ds_read_b128 v[158:161], v144 offset:3072
	v_add_u32_e32 v144, s87, v172
	ds_read_b128 v[162:165], v144
	ds_read_b128 v[166:169], v144 offset:1024
	ds_read_b128 v[176:179], v144 offset:2048
	ds_read_b128 v[180:183], v144 offset:3072
	s_add_u32 s10, s10, 0x100000
	s_addc_u32 s11, s11, 0
	s_mov_b32 m0, s66
	v_lshl_add_u64 v[224:225], s[10:11], 0, v[136:137]
	ds_read_b128 v[184:187], v175 offset:32768
	ds_read_b128 v[188:191], v175 offset:33792
	ds_read_b128 v[192:195], v175 offset:34816
	ds_read_b128 v[196:199], v175 offset:35840
	ds_read_b128 v[200:203], v175 offset:36864
	ds_read_b128 v[204:207], v175 offset:37888
	ds_read_b128 v[208:211], v175 offset:38912
	ds_read_b128 v[212:215], v175 offset:39936
	global_load_lds_dwordx4 v[224:225], off
	v_lshl_add_u64 v[224:225], s[10:11], 0, v[140:141]
	s_mov_b32 m0, s67
	s_nop 0
	global_load_lds_dwordx4 v[224:225], off
	s_waitcnt vmcnt(8)
	s_waitcnt lgkmcnt(0)
	s_barrier
	s_setprio 1
	v_mfma_f32_16x16x32_f16 v[124:127], v[128:131], v[184:187], v[124:127]
	v_mfma_f32_16x16x32_f16 v[120:123], v[154:157], v[184:187], v[120:123]
	v_mfma_f32_16x16x32_f16 v[108:111], v[128:131], v[192:195], v[108:111]
	v_mfma_f32_16x16x32_f16 v[104:107], v[154:157], v[192:195], v[104:107]
	v_mfma_f32_16x16x32_f16 v[92:95], v[128:131], v[200:203], v[92:95]
	v_mfma_f32_16x16x32_f16 v[88:91], v[154:157], v[200:203], v[88:91]
	v_mfma_f32_16x16x32_f16 v[76:79], v[128:131], v[208:211], v[76:79]
	v_mfma_f32_16x16x32_f16 v[72:75], v[154:157], v[208:211], v[72:75]
	v_mfma_f32_16x16x32_f16 v[124:127], v[132:135], v[188:191], v[124:127]
	v_mfma_f32_16x16x32_f16 v[120:123], v[158:161], v[188:191], v[120:123]
	v_mfma_f32_16x16x32_f16 v[108:111], v[132:135], v[196:199], v[108:111]
	v_mfma_f32_16x16x32_f16 v[104:107], v[158:161], v[196:199], v[104:107]
	v_mfma_f32_16x16x32_f16 v[92:95], v[132:135], v[204:207], v[92:95]
	v_mfma_f32_16x16x32_f16 v[88:91], v[158:161], v[204:207], v[88:91]
	v_mfma_f32_16x16x32_f16 v[76:79], v[132:135], v[212:215], v[76:79]
	v_mfma_f32_16x16x32_f16 v[72:75], v[158:161], v[212:215], v[72:75]
	s_setprio 0
	s_setprio 1
	v_mfma_f32_16x16x32_f16 v[116:119], v[162:165], v[184:187], v[116:119]
	v_mfma_f32_16x16x32_f16 v[112:115], v[176:179], v[184:187], v[112:115]
	v_mfma_f32_16x16x32_f16 v[100:103], v[162:165], v[192:195], v[100:103]
	v_mfma_f32_16x16x32_f16 v[96:99], v[176:179], v[192:195], v[96:99]
	v_mfma_f32_16x16x32_f16 v[84:87], v[162:165], v[200:203], v[84:87]
	v_mfma_f32_16x16x32_f16 v[80:83], v[176:179], v[200:203], v[80:83]
	v_mfma_f32_16x16x32_f16 v[68:71], v[162:165], v[208:211], v[68:71]
	v_mfma_f32_16x16x32_f16 v[64:67], v[176:179], v[208:211], v[64:67]
	v_mfma_f32_16x16x32_f16 v[116:119], v[166:169], v[188:191], v[116:119]
	v_mfma_f32_16x16x32_f16 v[112:115], v[180:183], v[188:191], v[112:115]
	v_mfma_f32_16x16x32_f16 v[100:103], v[166:169], v[196:199], v[100:103]
	v_mfma_f32_16x16x32_f16 v[96:99], v[180:183], v[196:199], v[96:99]
	v_mfma_f32_16x16x32_f16 v[84:87], v[166:169], v[204:207], v[84:87]
	v_mfma_f32_16x16x32_f16 v[80:83], v[180:183], v[204:207], v[80:83]
	v_mfma_f32_16x16x32_f16 v[68:71], v[166:169], v[212:215], v[68:71]
	v_mfma_f32_16x16x32_f16 v[64:67], v[180:183], v[212:215], v[64:67]
	s_setprio 0
	s_barrier
	s_add_i32 s10, s53, s23
	v_lshl_add_u64 v[170:171], v[170:171], 0, s[28:29]
	s_mov_b32 m0, s10
	ds_read_b128 v[184:187], v175 offset:49152
	ds_read_b128 v[188:191], v175 offset:50176
	ds_read_b128 v[192:195], v175 offset:51200
	ds_read_b128 v[196:199], v175 offset:52224
	ds_read_b128 v[200:203], v175 offset:53248
	ds_read_b128 v[204:207], v175 offset:54272
	ds_read_b128 v[208:211], v175 offset:55296
	ds_read_b128 v[212:215], v175 offset:56320
	global_load_lds_dwordx4 v[170:171], off
	s_add_i32 m0, s10, 0x2000
	s_add_u32 s8, s8, 0x100080
	v_lshl_add_u64 v[170:171], v[216:217], 0, s[28:29]
	s_addc_u32 s9, s9, 0
	s_add_i32 s10, s87, s23
	global_load_lds_dwordx4 v[170:171], off
	v_lshl_add_u64 v[170:171], s[8:9], 0, v[138:139]
	s_mov_b32 m0, s10
	s_nop 0
	global_load_lds_dwordx4 v[170:171], off
	v_lshl_add_u64 v[170:171], s[8:9], 0, v[142:143]
	s_add_i32 m0, s10, 0x2000
	s_nop 0
	global_load_lds_dwordx4 v[170:171], off
	v_lshl_add_u64 v[170:171], v[218:219], 0, s[28:29]
	s_mov_b32 m0, s18
	s_nop 0
	global_load_lds_dwordx4 v[170:171], off
	v_lshl_add_u64 v[170:171], v[220:221], 0, s[28:29]
	s_mov_b32 m0, s19
	s_nop 0
	global_load_lds_dwordx4 v[170:171], off
	s_waitcnt vmcnt(8)
	s_waitcnt lgkmcnt(0)
	s_barrier
	s_setprio 1
	v_mfma_f32_16x16x32_f16 v[60:63], v[128:131], v[184:187], v[60:63]
	v_mfma_f32_16x16x32_f16 v[56:59], v[154:157], v[184:187], v[56:59]
	v_mfma_f32_16x16x32_f16 v[44:47], v[128:131], v[192:195], v[44:47]
	v_mfma_f32_16x16x32_f16 v[40:43], v[154:157], v[192:195], v[40:43]
	v_mfma_f32_16x16x32_f16 v[28:31], v[128:131], v[200:203], v[28:31]
	v_mfma_f32_16x16x32_f16 v[24:27], v[154:157], v[200:203], v[24:27]
	v_mfma_f32_16x16x32_f16 v[12:15], v[128:131], v[208:211], v[12:15]
	v_mfma_f32_16x16x32_f16 v[8:11], v[154:157], v[208:211], v[8:11]
	v_mfma_f32_16x16x32_f16 v[60:63], v[132:135], v[188:191], v[60:63]
	v_mfma_f32_16x16x32_f16 v[56:59], v[158:161], v[188:191], v[56:59]
	v_mfma_f32_16x16x32_f16 v[44:47], v[132:135], v[196:199], v[44:47]
	v_mfma_f32_16x16x32_f16 v[40:43], v[158:161], v[196:199], v[40:43]
	v_mfma_f32_16x16x32_f16 v[28:31], v[132:135], v[204:207], v[28:31]
	v_mfma_f32_16x16x32_f16 v[24:27], v[158:161], v[204:207], v[24:27]
	v_mfma_f32_16x16x32_f16 v[12:15], v[132:135], v[212:215], v[12:15]
	v_mfma_f32_16x16x32_f16 v[8:11], v[158:161], v[212:215], v[8:11]
	s_setprio 0
	s_setprio 1
	v_mfma_f32_16x16x32_f16 v[52:55], v[162:165], v[184:187], v[52:55]
	v_mfma_f32_16x16x32_f16 v[48:51], v[176:179], v[184:187], v[48:51]
	v_mfma_f32_16x16x32_f16 v[36:39], v[162:165], v[192:195], v[36:39]
	v_mfma_f32_16x16x32_f16 v[32:35], v[176:179], v[192:195], v[32:35]
	v_mfma_f32_16x16x32_f16 v[20:23], v[162:165], v[200:203], v[20:23]
	v_mfma_f32_16x16x32_f16 v[16:19], v[176:179], v[200:203], v[16:19]
	v_mfma_f32_16x16x32_f16 v[4:7], v[162:165], v[208:211], v[4:7]
	v_mfma_f32_16x16x32_f16 v[0:3], v[176:179], v[208:211], v[0:3]
	v_mfma_f32_16x16x32_f16 v[52:55], v[166:169], v[188:191], v[52:55]
	v_mfma_f32_16x16x32_f16 v[48:51], v[180:183], v[188:191], v[48:51]
	v_mfma_f32_16x16x32_f16 v[36:39], v[166:169], v[196:199], v[36:39]
	v_mfma_f32_16x16x32_f16 v[32:35], v[180:183], v[196:199], v[32:35]
	v_mfma_f32_16x16x32_f16 v[20:23], v[166:169], v[204:207], v[20:23]
	v_mfma_f32_16x16x32_f16 v[16:19], v[180:183], v[204:207], v[16:19]
	v_mfma_f32_16x16x32_f16 v[4:7], v[166:169], v[212:215], v[4:7]
	v_mfma_f32_16x16x32_f16 v[0:3], v[180:183], v[212:215], v[0:3]
	s_setprio 0
	s_add_i32 s52, s52, 2
	s_add_u32 s6, s6, 0x100
	s_addc_u32 s7, s7, 0
	s_add_u32 s46, s46, 0x100
	s_addc_u32 s47, s47, 0
	s_cmp_gt_u32 s52, 61
	s_barrier
	s_cbranch_scc0 .LBB0_601
	s_and_b64 vcc, exec, s[30:31]
	s_cbranch_vccz .LBB0_604
	s_barrier

.LBB0_1741:
	v_add_u32_e32 v0, s59, v156
	ds_read_b128 v[132:135], v0
	ds_read_b128 v[136:139], v0 offset:1024
	ds_read_b128 v[140:143], v0 offset:2048
	ds_read_b128 v[144:147], v0 offset:3072
	v_add_u32_e32 v0, s60, v156
	s_add_u32 s72, s4, s30
	ds_read_b128 v[162:165], v0
	ds_read_b128 v[166:169], v0 offset:1024
	ds_read_b128 v[170:173], v0 offset:2048
	ds_read_b128 v[174:177], v0 offset:3072
	s_addc_u32 s73, s5, s31
	s_add_u32 s44, s72, 0x100
	s_addc_u32 s45, s73, 0
	s_add_u32 s46, s67, s30
	s_addc_u32 s47, s70, s31
	s_cmpk_eq_i32 s30, 0xf00
	s_cselect_b32 s45, s23, s45
	s_cselect_b32 s44, s63, s44
	s_cselect_b32 s47, s64, s47
	s_cselect_b32 s46, s65, s46
	v_mov_b32_e32 v0, v254
	ds_read_b128 v[178:181], v158
	ds_read_b128 v[182:185], v158 offset:1024
	ds_read_b128 v[186:189], v158 offset:2048
	ds_read_b128 v[190:193], v158 offset:3072
	ds_read_b128 v[194:197], v158 offset:4096
	ds_read_b128 v[198:201], v158 offset:5120
	ds_read_b128 v[210:213], v158 offset:6144
	ds_read_b128 v[214:217], v158 offset:7168
	s_add_i32 m0, s34, 0xc000
	v_lshl_add_u64 v[2:3], s[72:73], 0, v[0:1]
	v_lshl_add_u64 v[2:3], v[2:3], 0, s[12:13]
	v_mov_b32_e32 v0, v223
	global_load_lds_dwordx4 v[2:3], off
	s_add_i32 m0, s34, 0xe000
	v_lshl_add_u64 v[2:3], s[72:73], 0, v[0:1]
	v_lshl_add_u64 v[2:3], v[2:3], 0, s[12:13]
	global_load_lds_dwordx4 v[2:3], off
	s_waitcnt vmcnt(8)
	s_waitcnt lgkmcnt(0)
	s_barrier
	s_setprio 1
	v_mfma_scale_f32_16x16x128_f8f6f4 v[128:131], v[132:139], v[178:185], v[128:131], v159, v159 op_sel_hi:[0,0,0]
	v_mfma_scale_f32_16x16x128_f8f6f4 v[124:127], v[140:147], v[178:185], v[124:127], v159, v159 op_sel_hi:[0,0,0]
	v_mfma_scale_f32_16x16x128_f8f6f4 v[112:115], v[132:139], v[186:193], v[112:115], v159, v159 op_sel_hi:[0,0,0]
	v_mfma_scale_f32_16x16x128_f8f6f4 v[108:111], v[140:147], v[186:193], v[108:111], v159, v159 op_sel_hi:[0,0,0]
	v_mfma_scale_f32_16x16x128_f8f6f4 v[202:205], v[132:139], v[194:201], v[96:99], v159, v159 op_sel_hi:[0,0,0]
	v_mfma_scale_f32_16x16x128_f8f6f4 v[206:209], v[140:147], v[194:201], v[92:95], v159, v159 op_sel_hi:[0,0,0]
	v_mfma_scale_f32_16x16x128_f8f6f4 v[218:221], v[132:139], v[210:217], v[80:83], v159, v159 op_sel_hi:[0,0,0]
	v_mfma_scale_f32_16x16x128_f8f6f4 v[224:227], v[140:147], v[210:217], v[76:79], v159, v159 op_sel_hi:[0,0,0]
	s_setprio 0
	s_setprio 1
	v_mfma_scale_f32_16x16x128_f8f6f4 v[120:123], v[162:169], v[178:185], v[120:123], v159, v159 op_sel_hi:[0,0,0]
	v_mfma_scale_f32_16x16x128_f8f6f4 v[116:119], v[170:177], v[178:185], v[116:119], v159, v159 op_sel_hi:[0,0,0]
	v_mfma_scale_f32_16x16x128_f8f6f4 v[104:107], v[162:169], v[186:193], v[104:107], v159, v159 op_sel_hi:[0,0,0]
	v_mfma_scale_f32_16x16x128_f8f6f4 v[100:103], v[170:177], v[186:193], v[100:103], v159, v159 op_sel_hi:[0,0,0]
	v_mfma_scale_f32_16x16x128_f8f6f4 v[178:181], v[162:169], v[194:201], v[88:91], v159, v159 op_sel_hi:[0,0,0]
	v_mfma_scale_f32_16x16x128_f8f6f4 v[182:185], v[170:177], v[194:201], v[84:87], v159, v159 op_sel_hi:[0,0,0]
	v_mfma_scale_f32_16x16x128_f8f6f4 v[186:189], v[162:169], v[210:217], v[72:75], v159, v159 op_sel_hi:[0,0,0]
	v_mfma_scale_f32_16x16x128_f8f6f4 v[190:193], v[170:177], v[210:217], v[68:71], v159, v159 op_sel_hi:[0,0,0]
	s_setprio 0
	s_barrier
	v_mov_b32_e32 v0, v254
	s_add_i32 s72, s59, s33
	s_nop 2
	ds_read_b128 v[68:71], v158 offset:16384
	ds_read_b128 v[72:75], v158 offset:17408
	ds_read_b128 v[76:79], v158 offset:18432
	ds_read_b128 v[80:83], v158 offset:19456
	ds_read_b128 v[84:87], v158 offset:20480
	ds_read_b128 v[88:91], v158 offset:21504
	ds_read_b128 v[92:95], v158 offset:22528
	ds_read_b128 v[96:99], v158 offset:23552
	s_mov_b32 m0, s72
	s_nop 0
	global_load_lds_dwordx4 v0, s[46:47]
	v_mov_b32_e32 v0, v223
	s_add_i32 m0, s72, 0x2000
	s_add_u32 s72, s46, 0x80000
	global_load_lds_dwordx4 v0, s[46:47]
	s_addc_u32 s73, s47, 0
	v_mov_b32_e32 v0, v254
	s_add_i32 s75, s60, s33
	s_mov_b32 m0, s75
	s_nop 0
	global_load_lds_dwordx4 v0, s[72:73]
	v_mov_b32_e32 v0, v223
	s_add_i32 m0, s75, 0x2000
	s_nop 0
	global_load_lds_dwordx4 v0, s[72:73]
	v_mov_b32_e32 v0, v254
	s_mov_b32 m0, s34
	s_nop 0
	global_load_lds_dwordx4 v0, s[44:45]
	v_mov_b32_e32 v0, v223
	s_mov_b32 m0, s35
	s_nop 0
	global_load_lds_dwordx4 v0, s[44:45]
	s_waitcnt vmcnt(8)
	s_waitcnt lgkmcnt(0)
	s_barrier
	s_setprio 1
	v_mfma_scale_f32_16x16x128_f8f6f4 v[64:67], v[132:139], v[68:75], v[64:67], v159, v159 op_sel_hi:[0,0,0]
	v_mfma_scale_f32_16x16x128_f8f6f4 v[60:63], v[140:147], v[68:75], v[60:63], v159, v159 op_sel_hi:[0,0,0]
	v_mfma_scale_f32_16x16x128_f8f6f4 v[194:197], v[132:139], v[76:83], v[48:51], v159, v159 op_sel_hi:[0,0,0]
	v_mfma_scale_f32_16x16x128_f8f6f4 v[198:201], v[140:147], v[76:83], v[44:47], v159, v159 op_sel_hi:[0,0,0]
	v_mfma_scale_f32_16x16x128_f8f6f4 v[210:213], v[132:139], v[84:91], v[32:35], v159, v159 op_sel_hi:[0,0,0]
	v_mfma_scale_f32_16x16x128_f8f6f4 v[214:217], v[140:147], v[84:91], v[28:31], v159, v159 op_sel_hi:[0,0,0]
	v_mfma_scale_f32_16x16x128_f8f6f4 v[228:231], v[132:139], v[92:99], v[16:19], v159, v159 op_sel_hi:[0,0,0]
	v_mfma_scale_f32_16x16x128_f8f6f4 v[232:235], v[140:147], v[92:99], v[12:15], v159, v159 op_sel_hi:[0,0,0]
	s_setprio 0
	s_setprio 1
	v_mfma_scale_f32_16x16x128_f8f6f4 v[56:59], v[162:169], v[68:75], v[56:59], v159, v159 op_sel_hi:[0,0,0]
	v_mfma_scale_f32_16x16x128_f8f6f4 v[52:55], v[170:177], v[68:75], v[52:55], v159, v159 op_sel_hi:[0,0,0]
	v_mfma_scale_f32_16x16x128_f8f6f4 v[236:239], v[162:169], v[76:83], v[40:43], v159, v159 op_sel_hi:[0,0,0]
	v_mfma_scale_f32_16x16x128_f8f6f4 v[240:243], v[170:177], v[76:83], v[36:39], v159, v159 op_sel_hi:[0,0,0]
	v_mfma_scale_f32_16x16x128_f8f6f4 v[244:247], v[162:169], v[84:91], v[24:27], v159, v159 op_sel_hi:[0,0,0]
	v_mfma_scale_f32_16x16x128_f8f6f4 v[248:251], v[170:177], v[84:91], v[20:23], v159, v159 op_sel_hi:[0,0,0]
	v_mfma_scale_f32_16x16x128_f8f6f4 v[148:151], v[162:169], v[92:99], v[8:11], v159, v159 op_sel_hi:[0,0,0]
	v_mfma_scale_f32_16x16x128_f8f6f4 v[152:155], v[170:177], v[92:99], v[4:7], v159, v159 op_sel_hi:[0,0,0]
	s_setprio 0
	s_barrier
	s_add_i32 s75, 0, 0x18000
	v_add_u32_e32 v0, s75, v156
	s_add_i32 s76, 0, 0x1c000
	s_nop 1
	ds_read_b128 v[2:5], v0
	ds_read_b128 v[6:9], v0 offset:1024
	ds_read_b128 v[20:23], v0 offset:2048
	ds_read_b128 v[24:27], v0 offset:3072
	v_add_u32_e32 v0, s76, v156
	ds_read_b128 v[132:135], v0
	ds_read_b128 v[136:139], v0 offset:1024
	ds_read_b128 v[140:143], v0 offset:2048
	ds_read_b128 v[144:147], v0 offset:3072
	s_add_u32 s72, s44, 0x80000
	v_mov_b32_e32 v0, v254
	s_mov_b32 m0, s38
	ds_read_b128 v[10:13], v158 offset:32768
	ds_read_b128 v[14:17], v158 offset:33792
	ds_read_b128 v[28:31], v158 offset:34816
	ds_read_b128 v[32:35], v158 offset:35840
	ds_read_b128 v[36:39], v158 offset:36864
	ds_read_b128 v[40:43], v158 offset:37888
	ds_read_b128 v[44:47], v158 offset:38912
	ds_read_b128 v[48:51], v158 offset:39936
	s_addc_u32 s73, s45, 0
	s_nop 0
	global_load_lds_dwordx4 v0, s[72:73]
	v_mov_b32_e32 v0, v223
	s_mov_b32 m0, s39
	s_nop 0
	global_load_lds_dwordx4 v0, s[72:73]
	s_waitcnt vmcnt(8)
	s_waitcnt lgkmcnt(0)
	s_barrier
	s_setprio 1
	v_mfma_scale_f32_16x16x128_f8f6f4 v[128:131], v[2:9], v[10:17], v[128:131], v159, v159 op_sel_hi:[0,0,0]
	v_mfma_scale_f32_16x16x128_f8f6f4 v[124:127], v[20:27], v[10:17], v[124:127], v159, v159 op_sel_hi:[0,0,0]
	v_mfma_scale_f32_16x16x128_f8f6f4 v[112:115], v[2:9], v[28:35], v[112:115], v159, v159 op_sel_hi:[0,0,0]
	v_mfma_scale_f32_16x16x128_f8f6f4 v[108:111], v[20:27], v[28:35], v[108:111], v159, v159 op_sel_hi:[0,0,0]
	v_mfma_scale_f32_16x16x128_f8f6f4 v[96:99], v[2:9], v[36:43], v[202:205], v159, v159 op_sel_hi:[0,0,0]
	v_mfma_scale_f32_16x16x128_f8f6f4 v[92:95], v[20:27], v[36:43], v[206:209], v159, v159 op_sel_hi:[0,0,0]
	v_mfma_scale_f32_16x16x128_f8f6f4 v[80:83], v[2:9], v[44:51], v[218:221], v159, v159 op_sel_hi:[0,0,0]
	v_mfma_scale_f32_16x16x128_f8f6f4 v[76:79], v[20:27], v[44:51], v[224:227], v159, v159 op_sel_hi:[0,0,0]
	s_setprio 0
	s_setprio 1
	v_mfma_scale_f32_16x16x128_f8f6f4 v[120:123], v[132:139], v[10:17], v[120:123], v159, v159 op_sel_hi:[0,0,0]
	v_mfma_scale_f32_16x16x128_f8f6f4 v[116:119], v[140:147], v[10:17], v[116:119], v159, v159 op_sel_hi:[0,0,0]
	v_mfma_scale_f32_16x16x128_f8f6f4 v[104:107], v[132:139], v[28:35], v[104:107], v159, v159 op_sel_hi:[0,0,0]
	v_mfma_scale_f32_16x16x128_f8f6f4 v[100:103], v[140:147], v[28:35], v[100:103], v159, v159 op_sel_hi:[0,0,0]
	v_mfma_scale_f32_16x16x128_f8f6f4 v[88:91], v[132:139], v[36:43], v[178:181], v159, v159 op_sel_hi:[0,0,0]
	v_mfma_scale_f32_16x16x128_f8f6f4 v[84:87], v[140:147], v[36:43], v[182:185], v159, v159 op_sel_hi:[0,0,0]
	v_mfma_scale_f32_16x16x128_f8f6f4 v[72:75], v[132:139], v[44:51], v[186:189], v159, v159 op_sel_hi:[0,0,0]
	v_mfma_scale_f32_16x16x128_f8f6f4 v[68:71], v[140:147], v[44:51], v[190:193], v159, v159 op_sel_hi:[0,0,0]
	s_setprio 0
	s_barrier
	v_mov_b32_e32 v0, v254
	ds_read_b128 v[36:39], v158 offset:49152
	ds_read_b128 v[40:43], v158 offset:50176
	ds_read_b128 v[162:165], v158 offset:51200
	ds_read_b128 v[166:169], v158 offset:52224
	ds_read_b128 v[170:173], v158 offset:53248
	ds_read_b128 v[174:177], v158 offset:54272
	ds_read_b128 v[178:181], v158 offset:55296
	ds_read_b128 v[182:185], v158 offset:56320
	s_add_i32 s72, s75, s33
	v_lshl_add_u64 v[10:11], s[46:47], 0, v[0:1]
	v_lshl_add_u64 v[10:11], v[10:11], 0, s[10:11]
	s_mov_b32 m0, s72
	v_mov_b32_e32 v0, v223
	global_load_lds_dwordx4 v[10:11], off
	s_add_i32 m0, s72, 0x2000
	s_nop 0
	v_lshl_add_u64 v[10:11], s[46:47], 0, v[0:1]
	s_add_u32 s46, s46, 0x80080
	v_lshl_add_u64 v[10:11], v[10:11], 0, s[10:11]
	s_addc_u32 s47, s47, 0
	v_mov_b32_e32 v0, v254
	s_add_i32 s72, s76, s33
	global_load_lds_dwordx4 v[10:11], off
	s_mov_b32 m0, s72
	s_nop 0
	global_load_lds_dwordx4 v0, s[46:47]
	v_mov_b32_e32 v0, v223
	s_add_i32 m0, s72, 0x2000
	s_nop 0
	global_load_lds_dwordx4 v0, s[46:47]
	v_mov_b32_e32 v0, v254
	s_mov_b32 m0, s50
	v_lshl_add_u64 v[10:11], s[44:45], 0, v[0:1]
	v_lshl_add_u64 v[10:11], v[10:11], 0, s[10:11]
	v_mov_b32_e32 v0, v223
	global_load_lds_dwordx4 v[10:11], off
	s_mov_b32 m0, s51
	v_lshl_add_u64 v[10:11], s[44:45], 0, v[0:1]
	v_lshl_add_u64 v[10:11], v[10:11], 0, s[10:11]
	global_load_lds_dwordx4 v[10:11], off
	s_waitcnt vmcnt(8)
	s_waitcnt lgkmcnt(0)
	s_barrier
	s_setprio 1
	v_mfma_scale_f32_16x16x128_f8f6f4 v[64:67], v[2:9], v[36:43], v[64:67], v159, v159 op_sel_hi:[0,0,0]
	v_mfma_scale_f32_16x16x128_f8f6f4 v[60:63], v[20:27], v[36:43], v[60:63], v159, v159 op_sel_hi:[0,0,0]
	v_mfma_scale_f32_16x16x128_f8f6f4 v[48:51], v[2:9], v[162:169], v[194:197], v159, v159 op_sel_hi:[0,0,0]
	v_mfma_scale_f32_16x16x128_f8f6f4 v[44:47], v[20:27], v[162:169], v[198:201], v159, v159 op_sel_hi:[0,0,0]
	v_mfma_scale_f32_16x16x128_f8f6f4 v[32:35], v[2:9], v[170:177], v[210:213], v159, v159 op_sel_hi:[0,0,0]
	v_mfma_scale_f32_16x16x128_f8f6f4 v[28:31], v[20:27], v[170:177], v[214:217], v159, v159 op_sel_hi:[0,0,0]
	v_mfma_scale_f32_16x16x128_f8f6f4 v[16:19], v[2:9], v[178:185], v[228:231], v159, v159 op_sel_hi:[0,0,0]
	v_mfma_scale_f32_16x16x128_f8f6f4 v[12:15], v[20:27], v[178:185], v[232:235], v159, v159 op_sel_hi:[0,0,0]
	s_setprio 0
	s_setprio 1
	v_mfma_scale_f32_16x16x128_f8f6f4 v[56:59], v[132:139], v[36:43], v[56:59], v159, v159 op_sel_hi:[0,0,0]
	v_mfma_scale_f32_16x16x128_f8f6f4 v[52:55], v[140:147], v[36:43], v[52:55], v159, v159 op_sel_hi:[0,0,0]
	v_mfma_scale_f32_16x16x128_f8f6f4 v[40:43], v[132:139], v[162:169], v[236:239], v159, v159 op_sel_hi:[0,0,0]
	v_mfma_scale_f32_16x16x128_f8f6f4 v[36:39], v[140:147], v[162:169], v[240:243], v159, v159 op_sel_hi:[0,0,0]
	v_mfma_scale_f32_16x16x128_f8f6f4 v[24:27], v[132:139], v[170:177], v[244:247], v159, v159 op_sel_hi:[0,0,0]
	v_mfma_scale_f32_16x16x128_f8f6f4 v[20:23], v[140:147], v[170:177], v[248:251], v159, v159 op_sel_hi:[0,0,0]
	v_mfma_scale_f32_16x16x128_f8f6f4 v[8:11], v[132:139], v[178:185], v[148:151], v159, v159 op_sel_hi:[0,0,0]
	v_mfma_scale_f32_16x16x128_f8f6f4 v[4:7], v[140:147], v[178:185], v[152:155], v159, v159 op_sel_hi:[0,0,0]
	s_setprio 0
	s_add_i32 s71, s71, 2
	s_add_u32 s30, s30, 0x100
	s_addc_u32 s31, s31, 0
	s_cmp_gt_u32 s71, 29
	s_barrier
	s_cbranch_scc1 .LBB0_1744
